# combined: P1/Z load hoists, norm2 setup loads in flight, H/K epilogue rolling prefetch, E wait move, J loop DMA-before-ds_read
# speedup vs baseline: 1.0060x; 1.0060x over previous
.LBB0_776:
	s_cmp_lg_u32 s24, s9
	s_cselect_b64 s[22:23], -1, 0
	s_add_u32 s18, s12, 0x2c00
	s_addc_u32 s19, s13, 0
	s_cmp_eq_u32 s24, s9
	v_mov_b32_e32 v116, 0
	v_mov_b32_e32 v128, 0
	v_mov_b32_e32 v129, 0
	s_cbranch_scc1 .LBB0_778
	global_load_dwordx2 v[128:129], v2, s[18:19]

.Le_row2_skip:
	s_waitcnt vmcnt(0)
	s_branch .LBB0_772

.LBB0_1580:
	s_add_u32 s16, s12, 0xfff80080
	s_addc_u32 s17, s13, -1
	s_add_i32 s70, 0, 0x10000
	s_cmp_eq_u32 s69, 28
	s_cselect_b32 s19, s53, s17
	s_cselect_b32 s18, s64, s16
	s_cselect_b32 s17, s65, s68
	s_cselect_b32 s16, s66, s67
	s_add_i32 s72, 0, 0x14000
	v_lshl_add_u64 v[200:201], s[12:13], 0, v[160:161]
	s_add_i32 m0, s34, 0xc000
	s_nop 0
	global_load_lds_dwordx4 v[200:201], off
	v_lshl_add_u64 v[204:205], s[12:13], 0, v[162:163]
	s_add_i32 m0, s34, 0xe000
	s_nop 0
	global_load_lds_dwordx4 v[204:205], off
	v_add_u32_e32 v164, s70, v170
	ds_read_b128 v[172:175], v164
	ds_read_b128 v[176:179], v164 offset:1024
	ds_read_b128 v[182:185], v164 offset:2048
	ds_read_b128 v[186:189], v164 offset:3072
	v_add_u32_e32 v164, s72, v170
	ds_read_b128 v[190:193], v164
	ds_read_b128 v[194:197], v164 offset:1024
	ds_read_b128 v[206:209], v164 offset:2048
	ds_read_b128 v[212:215], v164 offset:3072
	ds_read_b128 v[216:219], v171
	ds_read_b128 v[220:223], v171 offset:1024
	ds_read_b128 v[224:227], v171 offset:2048
	ds_read_b128 v[228:231], v171 offset:3072
	ds_read_b128 v[232:235], v171 offset:4096
	ds_read_b128 v[236:239], v171 offset:5120
	ds_read_b128 v[240:243], v171 offset:6144
	ds_read_b128 v[244:247], v171 offset:7168
	s_waitcnt vmcnt(8)
	s_waitcnt lgkmcnt(0)
	s_barrier
	s_setprio 1
	s_waitcnt lgkmcnt(0)
	v_mfma_f32_16x16x32_bf16 v[152:155], v[172:175], v[216:219], v[152:155]
	v_mfma_f32_16x16x32_bf16 v[144:147], v[182:185], v[216:219], v[144:147]
	v_mfma_f32_16x16x32_bf16 v[136:139], v[172:175], v[224:227], v[136:139]
	v_mfma_f32_16x16x32_bf16 v[128:131], v[182:185], v[224:227], v[128:131]
	v_mfma_f32_16x16x32_bf16 v[120:123], v[172:175], v[232:235], v[120:123]
	v_mfma_f32_16x16x32_bf16 v[112:115], v[182:185], v[232:235], v[112:115]
	v_mfma_f32_16x16x32_bf16 v[104:107], v[172:175], v[240:243], v[104:107]
	v_mfma_f32_16x16x32_bf16 v[96:99], v[182:185], v[240:243], v[96:99]
	v_mfma_f32_16x16x32_bf16 v[152:155], v[176:179], v[220:223], v[152:155]
	v_mfma_f32_16x16x32_bf16 v[144:147], v[186:189], v[220:223], v[144:147]
	v_mfma_f32_16x16x32_bf16 v[136:139], v[176:179], v[228:231], v[136:139]
	v_mfma_f32_16x16x32_bf16 v[128:131], v[186:189], v[228:231], v[128:131]
	v_mfma_f32_16x16x32_bf16 v[120:123], v[176:179], v[236:239], v[120:123]
	v_mfma_f32_16x16x32_bf16 v[112:115], v[186:189], v[236:239], v[112:115]
	v_mfma_f32_16x16x32_bf16 v[104:107], v[176:179], v[244:247], v[104:107]
	v_mfma_f32_16x16x32_bf16 v[96:99], v[186:189], v[244:247], v[96:99]
	s_setprio 0
	s_setprio 1
	v_mfma_f32_16x16x32_bf16 v[148:151], v[190:193], v[216:219], v[148:151]
	v_mfma_f32_16x16x32_bf16 v[140:143], v[206:209], v[216:219], v[140:143]
	v_mfma_f32_16x16x32_bf16 v[132:135], v[190:193], v[224:227], v[132:135]
	v_mfma_f32_16x16x32_bf16 v[124:127], v[206:209], v[224:227], v[124:127]
	v_mfma_f32_16x16x32_bf16 v[116:119], v[190:193], v[232:235], v[116:119]
	v_mfma_f32_16x16x32_bf16 v[108:111], v[206:209], v[232:235], v[108:111]
	v_mfma_f32_16x16x32_bf16 v[100:103], v[190:193], v[240:243], v[100:103]
	v_mfma_f32_16x16x32_bf16 v[92:95], v[206:209], v[240:243], v[92:95]
	v_mfma_f32_16x16x32_bf16 v[148:151], v[194:197], v[220:223], v[148:151]
	v_mfma_f32_16x16x32_bf16 v[140:143], v[212:215], v[220:223], v[140:143]
	v_mfma_f32_16x16x32_bf16 v[132:135], v[194:197], v[228:231], v[132:135]
	v_mfma_f32_16x16x32_bf16 v[124:127], v[212:215], v[228:231], v[124:127]
	v_mfma_f32_16x16x32_bf16 v[116:119], v[194:197], v[236:239], v[116:119]
	v_mfma_f32_16x16x32_bf16 v[108:111], v[212:215], v[236:239], v[108:111]
	v_mfma_f32_16x16x32_bf16 v[100:103], v[194:197], v[244:247], v[100:103]
	v_mfma_f32_16x16x32_bf16 v[92:95], v[212:215], v[244:247], v[92:95]
	s_setprio 0
	s_barrier
	s_add_i32 s70, s70, s28
	v_lshl_add_u64 v[164:165], s[16:17], 0, v[2:3]
	s_mov_b32 m0, s70
	s_nop 0
	global_load_lds_dwordx4 v[164:165], off
	s_add_i32 m0, s70, 0x2000
	s_add_u32 s70, s16, 0x80000
	v_lshl_add_u64 v[200:201], s[16:17], 0, v[0:1]
	s_addc_u32 s71, s17, 0
	s_add_i32 s72, s72, s28
	global_load_lds_dwordx4 v[200:201], off
	v_lshl_add_u64 v[204:205], s[70:71], 0, v[2:3]
	s_mov_b32 m0, s72
	v_lshl_add_u64 v[248:249], s[18:19], 0, v[156:157]
	global_load_lds_dwordx4 v[204:205], off
	v_lshl_add_u64 v[204:205], s[70:71], 0, v[0:1]
	s_add_i32 m0, s72, 0x2000
	s_nop 0
	global_load_lds_dwordx4 v[204:205], off
	v_lshl_add_u64 v[204:205], s[18:19], 0, v[158:159]
	s_mov_b32 m0, s34
	s_nop 0
	global_load_lds_dwordx4 v[204:205], off
	s_mov_b32 m0, s35
	s_nop 0
	global_load_lds_dwordx4 v[248:249], off
	ds_read_b128 v[216:219], v171 offset:16384
	ds_read_b128 v[220:223], v171 offset:17408
	ds_read_b128 v[224:227], v171 offset:18432
	ds_read_b128 v[228:231], v171 offset:19456
	ds_read_b128 v[232:235], v171 offset:20480
	ds_read_b128 v[236:239], v171 offset:21504
	ds_read_b128 v[240:243], v171 offset:22528
	ds_read_b128 v[244:247], v171 offset:23552
	s_waitcnt vmcnt(8)
	s_waitcnt lgkmcnt(0)
	s_barrier
	s_setprio 1
	s_waitcnt lgkmcnt(0)
	v_mfma_f32_16x16x32_bf16 v[88:91], v[172:175], v[216:219], v[88:91]
	v_mfma_f32_16x16x32_bf16 v[80:83], v[182:185], v[216:219], v[80:83]
	v_mfma_f32_16x16x32_bf16 v[72:75], v[172:175], v[224:227], v[72:75]
	v_mfma_f32_16x16x32_bf16 v[64:67], v[182:185], v[224:227], v[64:67]
	v_mfma_f32_16x16x32_bf16 v[56:59], v[172:175], v[232:235], v[56:59]
	v_mfma_f32_16x16x32_bf16 v[48:51], v[182:185], v[232:235], v[48:51]
	v_mfma_f32_16x16x32_bf16 v[40:43], v[172:175], v[240:243], v[40:43]
	v_mfma_f32_16x16x32_bf16 v[32:35], v[182:185], v[240:243], v[32:35]
	v_mfma_f32_16x16x32_bf16 v[88:91], v[176:179], v[220:223], v[88:91]
	v_mfma_f32_16x16x32_bf16 v[80:83], v[186:189], v[220:223], v[80:83]
	v_mfma_f32_16x16x32_bf16 v[72:75], v[176:179], v[228:231], v[72:75]
	v_mfma_f32_16x16x32_bf16 v[64:67], v[186:189], v[228:231], v[64:67]
	v_mfma_f32_16x16x32_bf16 v[56:59], v[176:179], v[236:239], v[56:59]
	v_mfma_f32_16x16x32_bf16 v[48:51], v[186:189], v[236:239], v[48:51]
	v_mfma_f32_16x16x32_bf16 v[40:43], v[176:179], v[244:247], v[40:43]
	v_mfma_f32_16x16x32_bf16 v[32:35], v[186:189], v[244:247], v[32:35]
	s_setprio 0
	s_setprio 1
	v_mfma_f32_16x16x32_bf16 v[84:87], v[190:193], v[216:219], v[84:87]
	v_mfma_f32_16x16x32_bf16 v[76:79], v[206:209], v[216:219], v[76:79]
	v_mfma_f32_16x16x32_bf16 v[68:71], v[190:193], v[224:227], v[68:71]
	v_mfma_f32_16x16x32_bf16 v[60:63], v[206:209], v[224:227], v[60:63]
	v_mfma_f32_16x16x32_bf16 v[52:55], v[190:193], v[232:235], v[52:55]
	v_mfma_f32_16x16x32_bf16 v[44:47], v[206:209], v[232:235], v[44:47]
	v_mfma_f32_16x16x32_bf16 v[36:39], v[190:193], v[240:243], v[36:39]
	v_mfma_f32_16x16x32_bf16 v[28:31], v[206:209], v[240:243], v[28:31]
	v_mfma_f32_16x16x32_bf16 v[84:87], v[194:197], v[220:223], v[84:87]
	v_mfma_f32_16x16x32_bf16 v[76:79], v[212:215], v[220:223], v[76:79]
	v_mfma_f32_16x16x32_bf16 v[68:71], v[194:197], v[228:231], v[68:71]
	v_mfma_f32_16x16x32_bf16 v[60:63], v[212:215], v[228:231], v[60:63]
	v_mfma_f32_16x16x32_bf16 v[52:55], v[194:197], v[236:239], v[52:55]
	v_mfma_f32_16x16x32_bf16 v[44:47], v[212:215], v[236:239], v[44:47]
	v_mfma_f32_16x16x32_bf16 v[36:39], v[194:197], v[244:247], v[36:39]
	v_mfma_f32_16x16x32_bf16 v[28:31], v[212:215], v[244:247], v[28:31]
	s_setprio 0
	s_barrier
	s_add_i32 s70, 0, 0x18000
	s_add_i32 s71, 0, 0x1c000
	s_add_u32 s18, s18, 0x80000
	s_addc_u32 s19, s19, 0
	s_mov_b32 m0, s36
	v_lshl_add_u64 v[250:251], s[18:19], 0, v[158:159]
	global_load_lds_dwordx4 v[250:251], off
	v_lshl_add_u64 v[250:251], s[18:19], 0, v[156:157]
	s_mov_b32 m0, s37
	s_nop 0
	global_load_lds_dwordx4 v[250:251], off
	v_add_u32_e32 v186, s70, v170
	v_add_u32_e32 v212, s71, v170
	ds_read_b128 v[172:175], v186
	ds_read_b128 v[176:179], v186 offset:1024
	ds_read_b128 v[182:185], v186 offset:2048
	ds_read_b128 v[186:189], v186 offset:3072
	ds_read_b128 v[190:193], v212
	ds_read_b128 v[194:197], v212 offset:1024
	ds_read_b128 v[206:209], v212 offset:2048
	ds_read_b128 v[212:215], v212 offset:3072
	ds_read_b128 v[216:219], v171 offset:32768
	ds_read_b128 v[220:223], v171 offset:33792
	ds_read_b128 v[224:227], v171 offset:34816
	ds_read_b128 v[228:231], v171 offset:35840
	ds_read_b128 v[232:235], v171 offset:36864
	ds_read_b128 v[236:239], v171 offset:37888
	ds_read_b128 v[240:243], v171 offset:38912
	ds_read_b128 v[244:247], v171 offset:39936
	s_waitcnt vmcnt(8)
	s_waitcnt lgkmcnt(0)
	s_barrier
	s_setprio 1
	s_waitcnt lgkmcnt(0)
	v_mfma_f32_16x16x32_bf16 v[152:155], v[172:175], v[216:219], v[152:155]
	v_mfma_f32_16x16x32_bf16 v[144:147], v[182:185], v[216:219], v[144:147]
	v_mfma_f32_16x16x32_bf16 v[136:139], v[172:175], v[224:227], v[136:139]
	v_mfma_f32_16x16x32_bf16 v[128:131], v[182:185], v[224:227], v[128:131]
	v_mfma_f32_16x16x32_bf16 v[120:123], v[172:175], v[232:235], v[120:123]
	v_mfma_f32_16x16x32_bf16 v[112:115], v[182:185], v[232:235], v[112:115]
	v_mfma_f32_16x16x32_bf16 v[104:107], v[172:175], v[240:243], v[104:107]
	v_mfma_f32_16x16x32_bf16 v[96:99], v[182:185], v[240:243], v[96:99]
	v_mfma_f32_16x16x32_bf16 v[152:155], v[176:179], v[220:223], v[152:155]
	v_mfma_f32_16x16x32_bf16 v[144:147], v[186:189], v[220:223], v[144:147]
	v_mfma_f32_16x16x32_bf16 v[136:139], v[176:179], v[228:231], v[136:139]
	v_mfma_f32_16x16x32_bf16 v[128:131], v[186:189], v[228:231], v[128:131]
	v_mfma_f32_16x16x32_bf16 v[120:123], v[176:179], v[236:239], v[120:123]
	v_mfma_f32_16x16x32_bf16 v[112:115], v[186:189], v[236:239], v[112:115]
	v_mfma_f32_16x16x32_bf16 v[104:107], v[176:179], v[244:247], v[104:107]
	v_mfma_f32_16x16x32_bf16 v[96:99], v[186:189], v[244:247], v[96:99]
	s_setprio 0
	s_setprio 1
	v_mfma_f32_16x16x32_bf16 v[148:151], v[190:193], v[216:219], v[148:151]
	v_mfma_f32_16x16x32_bf16 v[140:143], v[206:209], v[216:219], v[140:143]
	v_mfma_f32_16x16x32_bf16 v[132:135], v[190:193], v[224:227], v[132:135]
	v_mfma_f32_16x16x32_bf16 v[124:127], v[206:209], v[224:227], v[124:127]
	v_mfma_f32_16x16x32_bf16 v[116:119], v[190:193], v[232:235], v[116:119]
	v_mfma_f32_16x16x32_bf16 v[108:111], v[206:209], v[232:235], v[108:111]
	v_mfma_f32_16x16x32_bf16 v[100:103], v[190:193], v[240:243], v[100:103]
	v_mfma_f32_16x16x32_bf16 v[92:95], v[206:209], v[240:243], v[92:95]
	v_mfma_f32_16x16x32_bf16 v[148:151], v[194:197], v[220:223], v[148:151]
	v_mfma_f32_16x16x32_bf16 v[140:143], v[212:215], v[220:223], v[140:143]
	v_mfma_f32_16x16x32_bf16 v[132:135], v[194:197], v[228:231], v[132:135]
	v_mfma_f32_16x16x32_bf16 v[124:127], v[212:215], v[228:231], v[124:127]
	v_mfma_f32_16x16x32_bf16 v[116:119], v[194:197], v[236:239], v[116:119]
	v_mfma_f32_16x16x32_bf16 v[108:111], v[212:215], v[236:239], v[108:111]
	v_mfma_f32_16x16x32_bf16 v[100:103], v[194:197], v[244:247], v[100:103]
	v_mfma_f32_16x16x32_bf16 v[92:95], v[212:215], v[244:247], v[92:95]
	s_setprio 0
	s_barrier
	s_add_i32 s18, s70, s28
	v_lshl_add_u64 v[164:165], v[164:165], 0, s[10:11]
	s_mov_b32 m0, s18
	s_nop 0
	global_load_lds_dwordx4 v[164:165], off
	s_add_i32 m0, s18, 0x2000
	s_add_u32 s16, s16, 0x80080
	v_lshl_add_u64 v[164:165], v[200:201], 0, s[10:11]
	s_addc_u32 s17, s17, 0
	s_add_i32 s18, s71, s28
	global_load_lds_dwordx4 v[164:165], off
	v_lshl_add_u64 v[164:165], s[16:17], 0, v[2:3]
	s_mov_b32 m0, s18
	s_nop 0
	global_load_lds_dwordx4 v[164:165], off
	v_lshl_add_u64 v[164:165], s[16:17], 0, v[0:1]
	s_add_i32 m0, s18, 0x2000
	s_nop 0
	global_load_lds_dwordx4 v[164:165], off
	v_lshl_add_u64 v[164:165], v[204:205], 0, s[10:11]
	s_mov_b32 m0, s59
	s_nop 0
	global_load_lds_dwordx4 v[164:165], off
	v_lshl_add_u64 v[164:165], v[248:249], 0, s[10:11]
	s_mov_b32 m0, s60
	s_nop 0
	global_load_lds_dwordx4 v[164:165], off
	ds_read_b128 v[216:219], v171 offset:49152
	ds_read_b128 v[220:223], v171 offset:50176
	ds_read_b128 v[224:227], v171 offset:51200
	ds_read_b128 v[228:231], v171 offset:52224
	ds_read_b128 v[232:235], v171 offset:53248
	ds_read_b128 v[236:239], v171 offset:54272
	ds_read_b128 v[240:243], v171 offset:55296
	ds_read_b128 v[244:247], v171 offset:56320
	s_waitcnt vmcnt(8)
	s_waitcnt lgkmcnt(0)
	s_barrier
	s_setprio 1
	s_waitcnt lgkmcnt(0)
	v_mfma_f32_16x16x32_bf16 v[88:91], v[172:175], v[216:219], v[88:91]
	v_mfma_f32_16x16x32_bf16 v[80:83], v[182:185], v[216:219], v[80:83]
	v_mfma_f32_16x16x32_bf16 v[72:75], v[172:175], v[224:227], v[72:75]
	v_mfma_f32_16x16x32_bf16 v[64:67], v[182:185], v[224:227], v[64:67]
	v_mfma_f32_16x16x32_bf16 v[56:59], v[172:175], v[232:235], v[56:59]
	v_mfma_f32_16x16x32_bf16 v[48:51], v[182:185], v[232:235], v[48:51]
	v_mfma_f32_16x16x32_bf16 v[40:43], v[172:175], v[240:243], v[40:43]
	v_mfma_f32_16x16x32_bf16 v[32:35], v[182:185], v[240:243], v[32:35]
	v_mfma_f32_16x16x32_bf16 v[88:91], v[176:179], v[220:223], v[88:91]
	v_mfma_f32_16x16x32_bf16 v[80:83], v[186:189], v[220:223], v[80:83]
	v_mfma_f32_16x16x32_bf16 v[72:75], v[176:179], v[228:231], v[72:75]
	v_mfma_f32_16x16x32_bf16 v[64:67], v[186:189], v[228:231], v[64:67]
	v_mfma_f32_16x16x32_bf16 v[56:59], v[176:179], v[236:239], v[56:59]
	v_mfma_f32_16x16x32_bf16 v[48:51], v[186:189], v[236:239], v[48:51]
	v_mfma_f32_16x16x32_bf16 v[40:43], v[176:179], v[244:247], v[40:43]
	v_mfma_f32_16x16x32_bf16 v[32:35], v[186:189], v[244:247], v[32:35]
	s_setprio 0
	s_setprio 1
	v_mfma_f32_16x16x32_bf16 v[84:87], v[190:193], v[216:219], v[84:87]
	v_mfma_f32_16x16x32_bf16 v[76:79], v[206:209], v[216:219], v[76:79]
	v_mfma_f32_16x16x32_bf16 v[68:71], v[190:193], v[224:227], v[68:71]
	v_mfma_f32_16x16x32_bf16 v[60:63], v[206:209], v[224:227], v[60:63]
	v_mfma_f32_16x16x32_bf16 v[52:55], v[190:193], v[232:235], v[52:55]
	v_mfma_f32_16x16x32_bf16 v[44:47], v[206:209], v[232:235], v[44:47]
	v_mfma_f32_16x16x32_bf16 v[36:39], v[190:193], v[240:243], v[36:39]
	v_mfma_f32_16x16x32_bf16 v[28:31], v[206:209], v[240:243], v[28:31]
	v_mfma_f32_16x16x32_bf16 v[84:87], v[194:197], v[220:223], v[84:87]
	v_mfma_f32_16x16x32_bf16 v[76:79], v[212:215], v[220:223], v[76:79]
	v_mfma_f32_16x16x32_bf16 v[68:71], v[194:197], v[228:231], v[68:71]
	v_mfma_f32_16x16x32_bf16 v[60:63], v[212:215], v[228:231], v[60:63]
	v_mfma_f32_16x16x32_bf16 v[52:55], v[194:197], v[236:239], v[52:55]
	v_mfma_f32_16x16x32_bf16 v[44:47], v[212:215], v[236:239], v[44:47]
	v_mfma_f32_16x16x32_bf16 v[36:39], v[194:197], v[244:247], v[36:39]
	v_mfma_f32_16x16x32_bf16 v[28:31], v[212:215], v[244:247], v[28:31]
	s_setprio 0
	s_barrier
	s_add_i32 s69, s69, 2
	s_add_u32 s12, s12, 0x100
	s_addc_u32 s13, s13, 0
	s_add_u32 s67, s67, 0x100
	s_addc_u32 s68, s68, 0
	s_cmp_gt_u32 s69, 29
	s_cbranch_scc0 .LBB0_1580
	s_and_b64 vcc, exec, s[50:51]
	s_cbranch_vccz .LBB0_1583
	s_barrier

.LBB0_1785:
	global_load_dwordx4 v[6:9], v[2:3], off offset:-2048
	global_load_dwordx4 v[12:15], v[2:3], off offset:-1024
	global_load_dwordx4 v[40:43], v[2:3], off
	global_load_dwordx4 v[64:67], v[2:3], off offset:1024
	s_load_dwordx2 s[10:11], s[4:5], 0xc8
	s_waitcnt lgkmcnt(0)
	global_load_dwordx4 v[68:71], v36, s[10:11] offset:16
	global_load_dwordx4 v[72:75], v36, s[10:11]
	global_load_dwordx4 v[76:79], v36, s[10:11] offset:2048
	global_load_dwordx4 v[80:83], v36, s[10:11] offset:2064
	global_load_dwordx4 v[84:87], v37, s[10:11]
	global_load_dwordx4 v[88:91], v37, s[10:11] offset:16
	global_load_dwordx4 v[92:95], v38, s[10:11]
	global_load_dwordx4 v[96:99], v38, s[10:11] offset:16
	s_waitcnt vmcnt(11)
	v_cvt_f32_f16 v4, v6
	v_add_co_u32_e32 v48, vcc, s13, v0
	s_add_i32 s12, s12, s2
	s_nop 0
	v_addc_co_u32_e32 v49, vcc, -1, v1, vcc
	s_cmpk_lt_i32 s12, 0x4000
	v_lshrrev_b32_e32 v5, 16, v6
	v_lshrrev_b32_e32 v10, 16, v8
	v_lshrrev_b32_e32 v11, 16, v9
	v_lshrrev_b32_e32 v6, 16, v7
	v_cvt_f32_f16 v5, v5
	v_cvt_f32_f16 v20, v7
	v_cvt_f32_f16 v21, v6
	v_cvt_f32_f16 v16, v8
	v_cvt_f32_f16 v17, v10
	v_cvt_f32_f16 v10, v9
	v_cvt_f32_f16 v11, v11
	s_waitcnt vmcnt(10)
	v_cvt_f32_f16 v8, v12
	v_mul_f32_e32 v39, v5, v5
	v_fmac_f32_e32 v39, v4, v4
	v_fmac_f32_e32 v39, v20, v20
	v_fmac_f32_e32 v39, v21, v21
	v_fmac_f32_e32 v39, v16, v16
	v_fmac_f32_e32 v39, v17, v17
	v_fmac_f32_e32 v39, v10, v10
	v_fmac_f32_e32 v39, v11, v11
	v_fmac_f32_e32 v39, v8, v8
	v_lshrrev_b32_e32 v6, 16, v12
	v_lshrrev_b32_e32 v7, 16, v13
	v_lshrrev_b32_e32 v19, 16, v15
	v_lshrrev_b32_e32 v12, 16, v14
	v_cvt_f32_f16 v9, v6
	v_cvt_f32_f16 v24, v13
	v_cvt_f32_f16 v25, v7
	v_cvt_f32_f16 v6, v14
	v_cvt_f32_f16 v7, v12
	v_cvt_f32_f16 v18, v15
	v_cvt_f32_f16 v19, v19
	s_waitcnt vmcnt(9)
	v_cvt_f32_f16 v14, v40
	v_fmac_f32_e32 v39, v9, v9
	v_fmac_f32_e32 v39, v24, v24
	v_fmac_f32_e32 v39, v25, v25
	v_fmac_f32_e32 v39, v6, v6
	v_fmac_f32_e32 v39, v7, v7
	v_fmac_f32_e32 v39, v18, v18
	v_fmac_f32_e32 v39, v19, v19
	v_fmac_f32_e32 v39, v14, v14
	v_lshrrev_b32_e32 v12, 16, v40
	v_lshrrev_b32_e32 v13, 16, v41
	v_lshrrev_b32_e32 v22, 16, v42
	v_lshrrev_b32_e32 v23, 16, v43
	v_cvt_f32_f16 v15, v12
	v_cvt_f32_f16 v26, v41
	v_cvt_f32_f16 v27, v13
	v_cvt_f32_f16 v12, v42
	v_cvt_f32_f16 v13, v22
	v_cvt_f32_f16 v22, v43
	v_cvt_f32_f16 v23, v23
	s_waitcnt vmcnt(8)
	v_cvt_f32_f16 v50, v64
	v_fmac_f32_e32 v39, v15, v15
	v_fmac_f32_e32 v39, v26, v26
	v_fmac_f32_e32 v39, v27, v27
	v_fmac_f32_e32 v39, v12, v12
	v_fmac_f32_e32 v39, v13, v13
	v_fmac_f32_e32 v39, v22, v22
	v_fmac_f32_e32 v39, v23, v23
	v_fmac_f32_e32 v39, v50, v50
	v_lshl_add_u64 v[2:3], v[2:3], 0, s[8:9]
	v_lshrrev_b32_e32 v44, 16, v64
	v_lshrrev_b32_e32 v40, 16, v65
	v_lshrrev_b32_e32 v45, 16, v66
	v_lshrrev_b32_e32 v46, 16, v67
	v_cvt_f32_f16 v51, v44
	v_cvt_f32_f16 v52, v65
	v_cvt_f32_f16 v53, v40
	v_cvt_f32_f16 v54, v66
	v_cvt_f32_f16 v55, v45
	v_cvt_f32_f16 v56, v67
	v_cvt_f32_f16 v57, v46
	v_fmac_f32_e32 v39, v51, v51
	v_fmac_f32_e32 v39, v52, v52
	v_fmac_f32_e32 v39, v53, v53
	v_fmac_f32_e32 v39, v54, v54
	v_pk_mul_f32 v[58:59], v[56:57], v[56:57]
	v_fmac_f32_e32 v39, v55, v55
	v_add_f32_e32 v39, v39, v58
	v_add_f32_e32 v39, v39, v59
	ds_bpermute_b32 v58, v28, v39
	s_waitcnt lgkmcnt(0)
	v_add_f32_e32 v39, v39, v58
	ds_bpermute_b32 v58, v29, v39
	s_waitcnt lgkmcnt(0)
	v_add_f32_e32 v39, v39, v58
	ds_bpermute_b32 v58, v30, v39
	s_waitcnt lgkmcnt(0)
	v_add_f32_e32 v39, v39, v58
	ds_bpermute_b32 v58, v31, v39
	s_waitcnt lgkmcnt(0)
	v_add_f32_e32 v39, v39, v58
	ds_bpermute_b32 v58, v32, v39
	s_waitcnt lgkmcnt(0)
	v_add_f32_e32 v39, v39, v58
	ds_bpermute_b32 v58, v33, v39
	s_waitcnt lgkmcnt(0)
	v_add_f32_e32 v39, v39, v58
	v_fmamk_f32 v39, v39, 0x3a000000, v34
	v_mul_f32_e32 v58, 0x4f800000, v39
	v_cmp_gt_f32_e32 vcc, s3, v39
	s_nop 1
	v_cndmask_b32_e32 v39, v39, v58, vcc
	v_sqrt_f32_e32 v58, v39
	s_nop 0
	v_add_u32_e32 v59, -1, v58
	v_add_u32_e32 v60, 1, v58
	v_fma_f32 v61, -v59, v58, v39
	v_fma_f32 v62, -v60, v58, v39
	v_cmp_ge_f32_e64 s[0:1], 0, v61
	s_nop 1
	v_cndmask_b32_e64 v58, v58, v59, s[0:1]
	v_cmp_lt_f32_e64 s[0:1], 0, v62
	s_nop 1
	v_cndmask_b32_e64 v58, v58, v60, s[0:1]
	v_mul_f32_e32 v59, 0x37800000, v58
	v_cndmask_b32_e32 v58, v58, v59, vcc
	v_cmp_class_f32_e32 vcc, v39, v35
	s_nop 1
	v_cndmask_b32_e32 v39, v58, v39, vcc
	v_div_scale_f32 v58, s[0:1], v39, v39, 1.0
	v_rcp_f32_e32 v60, v58
	v_div_scale_f32 v59, vcc, 1.0, v39, 1.0
	v_fma_f32 v61, -v58, v60, 1.0
	v_fmac_f32_e32 v60, v61, v60
	v_mul_f32_e32 v61, v59, v60
	v_fma_f32 v62, -v58, v61, v59
	v_fmac_f32_e32 v61, v62, v60
	v_fma_f32 v58, -v58, v61, v59
	v_div_fmas_f32 v58, v58, v60, v61
	v_div_fixup_f32 v58, v58, v39, 1.0
	v_pk_mul_f32 v[4:5], v[58:59], v[4:5] op_sel_hi:[0,1]
	v_pk_mul_f32 v[20:21], v[58:59], v[20:21] op_sel_hi:[0,1]
	v_pk_mul_f32 v[16:17], v[58:59], v[16:17] op_sel_hi:[0,1]
	v_pk_mul_f32 v[10:11], v[58:59], v[10:11] op_sel_hi:[0,1]
	s_waitcnt vmcnt(6)
	v_pk_mul_f32 v[46:47], v[74:75], v[20:21]
	v_pk_mul_f32 v[44:45], v[72:73], v[4:5]
	v_pk_mul_f32 v[42:43], v[70:71], v[10:11]
	v_pk_mul_f32 v[40:41], v[68:69], v[16:17]
	global_store_dwordx4 v[48:49], v[44:47], off offset:-2064
	global_store_dwordx4 v[48:49], v[40:43], off offset:-2048
	v_pk_mul_f32 v[10:11], v[58:59], v[24:25] op_sel_hi:[0,1]
	v_pk_mul_f32 v[4:5], v[58:59], v[8:9] op_sel_hi:[0,1]
	v_pk_mul_f32 v[16:17], v[58:59], v[18:19] op_sel_hi:[0,1]
	v_pk_mul_f32 v[8:9], v[58:59], v[6:7] op_sel_hi:[0,1]
	v_pk_mul_f32 v[14:15], v[58:59], v[14:15] op_sel_hi:[0,1]
	v_pk_mul_f32 v[18:19], v[58:59], v[22:23] op_sel_hi:[0,1]
	v_pk_mul_f32 v[12:13], v[58:59], v[12:13] op_sel_hi:[0,1]
	s_waitcnt vmcnt(6)
	v_pk_mul_f32 v[4:5], v[76:77], v[4:5]
	v_pk_mul_f32 v[6:7], v[78:79], v[10:11]
	v_pk_mul_f32 v[8:9], v[80:81], v[8:9]
	v_pk_mul_f32 v[10:11], v[82:83], v[16:17]
	global_store_dwordx4 v[48:49], v[4:7], off offset:-16
	global_store_dwordx4 v[0:1], v[8:11], off offset:-4096
	v_pk_mul_f32 v[16:17], v[58:59], v[26:27] op_sel_hi:[0,1]
	s_waitcnt vmcnt(6)
	v_pk_mul_f32 v[4:5], v[84:85], v[14:15]
	v_pk_mul_f32 v[6:7], v[86:87], v[16:17]
	v_pk_mul_f32 v[8:9], v[88:89], v[12:13]
	v_pk_mul_f32 v[10:11], v[90:91], v[18:19]
	global_store_dwordx4 v[0:1], v[4:7], off offset:-2064
	global_store_dwordx4 v[0:1], v[8:11], off offset:-2048
	v_pk_mul_f32 v[12:13], v[58:59], v[52:53] op_sel_hi:[0,1]
	v_pk_mul_f32 v[14:15], v[58:59], v[50:51] op_sel_hi:[0,1]
	v_pk_mul_f32 v[16:17], v[58:59], v[56:57] op_sel_hi:[0,1]
	v_pk_mul_f32 v[18:19], v[58:59], v[54:55] op_sel_hi:[0,1]
	s_waitcnt vmcnt(6)
	v_pk_mul_f32 v[4:5], v[92:93], v[14:15]
	v_pk_mul_f32 v[6:7], v[94:95], v[12:13]
	v_pk_mul_f32 v[8:9], v[96:97], v[18:19]
	v_pk_mul_f32 v[10:11], v[98:99], v[16:17]
	global_store_dwordx4 v[0:1], v[4:7], off offset:-16
	global_store_dwordx4 v[0:1], v[8:11], off
	v_lshl_add_u64 v[0:1], v[0:1], 0, s[6:7]
	s_cbranch_scc1 .LBB0_1785
